# nt hints only on mc_item<2> Q staging loads and gate loads (Y stores back to default policy)
# speedup vs baseline: 1.0056x; 1.0056x over previous
; __device__ __forceinline__ float siluf(float x) { return x * __builtin_amdgcn_rcpf(1.0f + __expf(-x)); }
; #define BSYNC() do { asm volatile("s_waitcnt vmcnt(0) lgkmcnt(0)" ::: "memory"); __syncthreads(); } while (0)
; template <int TY> __device__ __forceinline__ void mc_item(const Params& p, ldsp lds, int item) {
;     ...
;     BSYNC();
; #pragma unroll
;     for (int tk = 0; tk < 4; ++tk) { float s = 0.f;
; #pragma unroll
;         for (int w = 0; w < 8; ++w) s += RED[w * 64 + 16 * tk + l15];
;         rstd[tk] = rsqrtf(s * (1.0f / DV) + EPS); }
;     const float* nwp = TY == 0 ? p.in[12] : (TY == 1 ? p.in[14] : p.in[17]);
;     const int goff = TY == 0 ? E_RA + h * 128 : (TY == 1 ? E_GB + h * 128 : O_G + h * 512);
;     constexpr int LDY = TY == 2 ? 2048 : 1024; const int ycol = TY == 0 ? h * 128 : (TY == 1 ? 512 + h * 128 : h * 512);
;     bf16_t* Y = (bf16_t*)(p.ws + WS_Y);
; #pragma unroll
;     for (int ei = 0; ei < ET; ++ei) { const int e0 = 16 * (wave * ET + ei) + 4 * q4; const f32x4 w4 = *(const f32x4*)(nwp + e0);
; #pragma unroll
;         for (int tk = 0; tk < 4; ++tk) { const size_t row = (size_t)row0 + 16 * tk + l15;
;             const u32x2 gw = *(const u32x2*)(Pb + row * PP + goff + e0);
;             const float g0 = bf2f(gw.x & 0xffffu), g1 = bf2f(gw.x >> 16), g2 = bf2f(gw.y & 0xffffu), g3 = bf2f(gw.y >> 16);
;             const f32x4 v = acc[ei][tk] * rstd[tk] * w4;
;             float y0 = v[0] * siluf(g0), y1 = v[1] * siluf(g1), y2 = v[2] * siluf(g2), y3 = v[3] * siluf(g3);
.LBB0_877:
	s_or_b64 exec, exec, s[0:1]
	v_or_b32_e32 v72, s9, v151
	s_lshl_b32 s9, s59, 1
	s_add_u32 s0, s26, s9
	s_addc_u32 s1, s27, 0
	v_or_b32_e32 v84, s58, v150
	v_mov_b64_e32 v[90:91], s[0:1]
	s_waitcnt lgkmcnt(0)
	v_mad_i64_i32 v[62:63], s[0:1], v84, s56, v[90:91]
	v_ashrrev_i32_e32 v73, 31, v72
	v_lshl_add_u64 v[74:75], v[62:63], 0, s[48:49]
	v_lshlrev_b64 v[82:83], 1, v[72:73]
	v_lshl_add_u64 v[76:77], v[74:75], 0, v[82:83]
	s_waitcnt vmcnt(0) lgkmcnt(0)
	s_barrier
	global_load_dwordx2 v[186:187], v[76:77], off nt
	v_lshl_add_u64 v[188:189], v[72:73], 2, s[62:63]
	global_load_dwordx4 v[190:193], v[188:189], off
	v_or_b32_e32 v194, s58, v146
	v_mad_i64_i32 v[196:197], s[0:1], v194, s56, v[90:91]
	v_lshl_add_u64 v[198:199], v[196:197], 0, s[48:49]
	v_lshl_add_u64 v[200:201], v[198:199], 0, v[82:83]
	global_load_dwordx2 v[202:203], v[200:201], off nt
	v_or_b32_e32 v204, 32, v84
	v_mad_i64_i32 v[206:207], s[0:1], v204, s56, v[90:91]
	v_lshl_add_u64 v[208:209], v[206:207], 0, s[48:49]
	v_lshl_add_u64 v[210:211], v[208:209], 0, v[82:83]
	v_or_b32_e32 v212, 48, v84
	global_load_dwordx2 v[214:215], v[210:211], off nt
	v_mad_i64_i32 v[216:217], s[0:1], v212, s56, v[90:91]
	v_lshl_add_u64 v[218:219], v[216:217], 0, s[48:49]
	v_lshl_add_u64 v[220:221], v[218:219], 0, v[82:83]
	global_load_dwordx2 v[222:223], v[220:221], off nt
	v_or_b32_e32 v224, 16, v72
	v_ashrrev_i32_e32 v225, 31, v224
	v_lshlrev_b64 v[226:227], 1, v[224:225]
	v_lshl_add_u64 v[228:229], v[74:75], 0, v[226:227]
	global_load_dwordx2 v[230:231], v[228:229], off nt
	global_load_dwordx4 v[232:235], v[188:189], off offset:64
	v_lshl_add_u64 v[236:237], v[198:199], 0, v[226:227]
	global_load_dwordx2 v[238:239], v[236:237], off nt
	v_lshl_add_u64 v[240:241], v[208:209], 0, v[226:227]
	global_load_dwordx2 v[242:243], v[240:241], off nt
	v_lshl_add_u64 v[244:245], v[218:219], 0, v[226:227]
	global_load_dwordx2 v[246:247], v[244:245], off nt
	v_or_b32_e32 v248, 32, v72
	v_ashrrev_i32_e32 v249, 31, v248
	v_lshlrev_b64 v[120:121], 1, v[248:249]
	v_lshl_add_u64 v[122:123], v[74:75], 0, v[120:121]
	global_load_dwordx2 v[124:125], v[122:123], off nt
	v_lshl_add_u64 v[126:127], v[198:199], 0, v[120:121]
	global_load_dwordx4 v[128:131], v[188:189], off offset:128
	global_load_dwordx2 v[132:133], v[126:127], off nt
	v_lshl_add_u64 v[134:135], v[208:209], 0, v[120:121]
	global_load_dwordx2 v[136:137], v[134:135], off nt
	v_lshl_add_u64 v[140:141], v[218:219], 0, v[120:121]
	global_load_dwordx2 v[142:143], v[140:141], off nt
	v_or_b32_e32 v144, 48, v72
	v_ashrrev_i32_e32 v145, 31, v144
	v_lshlrev_b64 v[148:149], 1, v[144:145]
	v_lshl_add_u64 v[152:153], v[74:75], 0, v[148:149]
	global_load_dwordx2 v[154:155], v[152:153], off nt
	v_lshl_add_u64 v[156:157], v[198:199], 0, v[148:149]
	global_load_dwordx4 v[172:175], v[188:189], off offset:192
	global_load_dwordx2 v[158:159], v[156:157], off nt
	v_lshl_add_u64 v[162:163], v[208:209], 0, v[148:149]
	global_load_dwordx2 v[166:167], v[162:163], off nt
	v_lshl_add_u64 v[176:177], v[218:219], 0, v[148:149]
	global_load_dwordx2 v[178:179], v[176:177], off nt
	v_lshl_add_u64 v[70:71], v[72:73], 2, s[62:63]
	v_lshl_add_u32 v16, v150, 2, 0
	v_add_u32_e32 v16, 0x24c00, v16
	ds_read2_b32 v[76:77], v16 offset1:16
	ds_read2_b32 v[80:81], v16 offset0:64 offset1:80
	ds_read2_b32 v[86:87], v16 offset0:128 offset1:144
	ds_read2_b32 v[108:109], v16 offset0:192 offset1:208
	v_add_u32_e32 v73, 0x400, v16
	s_waitcnt lgkmcnt(3)
	v_mov_b32_e32 v118, v77
	v_mov_b32_e32 v119, v76
	s_waitcnt lgkmcnt(2)
	v_mov_b32_e32 v76, v81
	v_mov_b32_e32 v77, v80
	s_waitcnt lgkmcnt(1)
	v_mov_b32_e32 v80, v87
	v_mov_b32_e32 v81, v86
	s_waitcnt lgkmcnt(0)
	v_mov_b32_e32 v86, v109
	v_mov_b32_e32 v87, v108
	v_pk_add_f32 v[108:109], v[118:119], 0 op_sel_hi:[1,0]
	ds_read2_b32 v[106:107], v16 offset0:32 offset1:48
	ds_read2_b32 v[102:103], v16 offset0:96 offset1:112
	ds_read2_b32 v[98:99], v16 offset0:160 offset1:176
	ds_read2_b32 v[94:95], v16 offset0:224 offset1:240
	ds_read2_b32 v[110:111], v73 offset1:16
	ds_read2_b32 v[112:113], v73 offset0:64 offset1:80
	ds_read2_b32 v[114:115], v73 offset0:128 offset1:144
	ds_read2_b32 v[116:117], v73 offset0:192 offset1:208
	ds_read2_b32 v[104:105], v73 offset0:32 offset1:48
	ds_read2_b32 v[100:101], v73 offset0:96 offset1:112
	ds_read2_b32 v[96:97], v73 offset0:160 offset1:176
	ds_read2_b32 v[92:93], v73 offset0:224 offset1:240
	v_pk_add_f32 v[76:77], v[108:109], v[76:77]
	s_waitcnt lgkmcnt(7)
	v_mov_b32_e32 v118, v111
	v_pk_add_f32 v[76:77], v[76:77], v[80:81]
	v_mov_b32_e32 v119, v110
	v_pk_add_f32 v[76:77], v[76:77], v[86:87]
	s_waitcnt lgkmcnt(6)
	v_mov_b32_e32 v110, v113
	v_mov_b32_e32 v111, v112
	v_pk_add_f32 v[76:77], v[76:77], v[118:119]
	s_waitcnt lgkmcnt(5)
	v_mov_b32_e32 v112, v115
	v_mov_b32_e32 v113, v114
	v_pk_add_f32 v[76:77], v[76:77], v[110:111]
	s_mov_b32 s0, 0x358637bd
	s_waitcnt lgkmcnt(4)
	v_mov_b32_e32 v114, v117
	v_mov_b32_e32 v115, v116
	v_pk_add_f32 v[76:77], v[76:77], v[112:113]
	v_mov_b64_e32 v[88:89], s[0:1]
	v_mov_b32_e32 v85, s8
	v_pk_add_f32 v[76:77], v[76:77], v[114:115]
	s_mov_b32 s8, 0x3b000000
	v_pk_fma_f32 v[76:77], v[76:77], s[8:9], v[88:89] op_sel_hi:[1,0,0]
	s_add_u32 s0, s61, s9
	v_mul_f32_e32 v16, 0x4b800000, v77
	v_cmp_gt_f32_e32 vcc, s33, v77
	v_readlane_b32 s1, v253, 31
	s_addc_u32 s1, s1, 0
	v_cndmask_b32_e32 v16, v77, v16, vcc
	v_rsq_f32_e32 v16, v16
	v_lshl_add_u64 v[86:87], s[0:1], 0, v[82:83]
	s_add_i32 s37, s37, s70
	s_add_i32 s36, s36, s70
	v_mul_f32_e32 v73, 0x45800000, v16
	v_cndmask_b32_e32 v16, v16, v73, vcc
	v_pk_mul_f32 v[66:67], v[66:67], v[16:17] op_sel_hi:[1,0]
	v_pk_mul_f32 v[68:69], v[68:69], v[16:17] op_sel_hi:[1,0]
	v_cmp_gt_f32_e32 vcc, s33, v76
	v_pk_mul_f32 v[46:47], v[46:47], v[16:17] op_sel_hi:[1,0]
	v_pk_mul_f32 v[48:49], v[48:49], v[16:17] op_sel_hi:[1,0]
	v_pk_mul_f32 v[30:31], v[30:31], v[16:17] op_sel_hi:[1,0]
	v_pk_mul_f32 v[32:33], v[32:33], v[16:17] op_sel_hi:[1,0]
	v_pk_mul_f32 v[12:13], v[12:13], v[16:17] op_sel_hi:[1,0]
	v_pk_mul_f32 v[14:15], v[14:15], v[16:17] op_sel_hi:[1,0]
	s_cmpk_lt_i32 s37, 0x400
	s_waitcnt vmcnt(0)
; __device__ __forceinline__ unsigned pk2(float lo, float hi) { return pg8::cvt_pk_bf16(lo, hi); }
; __device__ __forceinline__ float siluf(float x) { return x * __builtin_amdgcn_rcpf(1.0f + __expf(-x)); }
; template <int TY> __device__ __forceinline__ void mc_item(const Params& p, ldsp lds, int item) {
;     ...
;     for (int ei = 0; ei < ET; ++ei) { const int e0 = 16 * (wave * ET + ei) + 4 * q4; const f32x4 w4 = *(const f32x4*)(nwp + e0);
; #pragma unroll
;         for (int tk = 0; tk < 4; ++tk) { const size_t row = (size_t)row0 + 16 * tk + l15;
;             const u32x2 gw = *(const u32x2*)(Pb + row * PP + goff + e0);
;             const float g0 = bf2f(gw.x & 0xffffu), g1 = bf2f(gw.x >> 16), g2 = bf2f(gw.y & 0xffffu), g3 = bf2f(gw.y >> 16);
;             const f32x4 v = acc[ei][tk] * rstd[tk] * w4;
;             float y0 = v[0] * siluf(g0), y1 = v[1] * siluf(g1), y2 = v[2] * siluf(g2), y3 = v[3] * siluf(g3);
;     ...
;             if (!(fabsf(y0) < 1e30f)) y0 = 0.f; if (!(fabsf(y1) < 1e30f)) y1 = 0.f; if (!(fabsf(y2) < 1e30f)) y2 = 0.f; if (!(fabsf(y3) < 1e30f)) y3 = 0.f;
;     ...
;             u32x2 o; o.x = pk2(y0, y1); o.y = pk2(y2, y3);
;             *(u32x2*)(Y + row * LDY + ycol + e0) = o; } }
	v_lshlrev_b32_e32 v73, 16, v186
	v_mul_f32_e32 v80, 0xbfb8aa3b, v73
	v_exp_f32_e32 v80, v80
	v_and_b32_e32 v77, 0xffff0000, v186
	v_lshlrev_b32_e32 v78, 16, v187
	v_and_b32_e32 v79, 0xffff0000, v187
	v_mul_f32_e32 v81, 0xbfb8aa3b, v77
	v_mul_f32_e32 v108, 0xbfb8aa3b, v78
	v_mul_f32_e32 v109, 0xbfb8aa3b, v79
	v_exp_f32_e32 v81, v81
	v_add_f32_e32 v80, 1.0, v80
	v_exp_f32_e32 v108, v108
	v_exp_f32_e32 v109, v109
	v_rcp_f32_e32 v80, v80
	v_add_f32_e32 v81, 1.0, v81
	v_pk_mul_f32 v[66:67], v[66:67], v[190:191]
	v_add_f32_e32 v108, 1.0, v108
	v_rcp_f32_e32 v81, v81
	v_add_f32_e32 v109, 1.0, v109
	v_mul_f32_e32 v73, v80, v73
	v_rcp_f32_e32 v108, v108
	v_mul_f32_e32 v66, v66, v73
	v_rcp_f32_e32 v73, v109
	v_mul_f32_e32 v77, v81, v77
	v_pk_mul_f32 v[68:69], v[68:69], v[192:193]
	v_mul_f32_e32 v67, v67, v77
	v_mul_f32_e32 v77, v108, v78
	v_mul_f32_e32 v73, v73, v79
	v_mul_f32_e32 v68, v68, v77
	v_mul_f32_e32 v69, v69, v73
	v_cvt_pk_bf16_f32 v66, v66, v67
	v_cvt_pk_bf16_f32 v67, v68, v69
	v_lshlrev_b64 v[68:69], 12, v[84:85]
	v_lshl_add_u64 v[78:79], v[86:87], 0, v[68:69]
	global_store_dwordx2 v[78:79], v[66:67], off
	v_or_b32_e32 v66, s58, v146
	v_mad_i64_i32 v[68:69], s[0:1], v66, s56, v[90:91]
	v_lshl_add_u64 v[80:81], v[68:69], 0, s[48:49]
	v_lshl_add_u64 v[68:69], v[80:81], 0, v[82:83]
	v_mul_f32_e32 v73, 0x4b800000, v76
	v_cndmask_b32_e32 v73, v76, v73, vcc
	v_rsq_f32_e32 v73, v73
	v_mov_b32_e32 v67, v85
	v_or_b32_e32 v108, 32, v84
	v_lshlrev_b64 v[66:67], 12, v[66:67]
	v_mul_f32_e32 v76, 0x45800000, v73
	v_cndmask_b32_e32 v76, v73, v76, vcc
	v_pk_mul_f32 v[58:59], v[58:59], v[76:77] op_sel_hi:[1,0]
	v_pk_mul_f32 v[60:61], v[60:61], v[76:77] op_sel_hi:[1,0]
	v_mad_i64_i32 v[68:69], s[0:1], v108, s56, v[90:91]
	v_pk_mul_f32 v[58:59], v[58:59], v[190:191]
	v_lshl_add_u64 v[68:69], v[68:69], 0, s[48:49]
	v_lshl_add_u64 v[66:67], v[86:87], 0, v[66:67]
	v_pk_mul_f32 v[60:61], v[60:61], v[192:193]
	v_lshl_add_u64 v[112:113], v[68:69], 0, v[82:83]
	v_or_b32_e32 v84, 48, v84
	v_lshlrev_b32_e32 v73, 16, v202
	v_and_b32_e32 v77, 0xffff0000, v202
	v_lshlrev_b32_e32 v109, 16, v203
	v_and_b32_e32 v110, 0xffff0000, v203
	v_mul_f32_e32 v111, 0xbfb8aa3b, v73
	v_mul_f32_e32 v114, 0xbfb8aa3b, v77
	v_mul_f32_e32 v115, 0xbfb8aa3b, v109
	v_mul_f32_e32 v116, 0xbfb8aa3b, v110
	v_exp_f32_e32 v111, v111
	v_exp_f32_e32 v114, v114
	v_exp_f32_e32 v115, v115
	v_exp_f32_e32 v116, v116
	v_add_f32_e32 v111, 1.0, v111
	v_add_f32_e32 v114, 1.0, v114
	v_add_f32_e32 v115, 1.0, v115
	v_add_f32_e32 v116, 1.0, v116
	v_rcp_f32_e32 v111, v111
	v_rcp_f32_e32 v114, v114
	v_rcp_f32_e32 v115, v115
	v_rcp_f32_e32 v116, v116
	v_mul_f32_e32 v73, v111, v73
	v_mul_f32_e32 v77, v114, v77
	v_mul_f32_e32 v109, v115, v109
	v_mul_f32_e32 v110, v116, v110
	v_mul_f32_e32 v58, v58, v73
	v_mul_f32_e32 v59, v59, v77
	v_mul_f32_e32 v60, v60, v109
	v_mul_f32_e32 v61, v61, v110
	v_cvt_pk_bf16_f32 v58, v58, v59
	v_cvt_pk_bf16_f32 v59, v60, v61
	global_store_dwordx2 v[66:67], v[58:59], off
	v_mad_i64_i32 v[60:61], s[0:1], v84, s56, v[90:91]
	v_mov_b32_e32 v90, v107
	v_mov_b32_e32 v91, v106
	v_mov_b32_e32 v106, v103
	v_mov_b32_e32 v107, v102
	v_pk_add_f32 v[90:91], v[90:91], 0 op_sel_hi:[1,0]
	v_mov_b32_e32 v102, v99
	v_mov_b32_e32 v103, v98
	v_pk_add_f32 v[90:91], v[90:91], v[106:107]
	v_mov_b32_e32 v98, v95
	v_mov_b32_e32 v99, v94
	v_pk_add_f32 v[90:91], v[90:91], v[102:103]
	s_waitcnt lgkmcnt(3)
	v_mov_b32_e32 v94, v105
	v_mov_b32_e32 v95, v104
	v_pk_add_f32 v[90:91], v[90:91], v[98:99]
	s_waitcnt lgkmcnt(2)
	v_mov_b32_e32 v104, v101
	v_mov_b32_e32 v105, v100
	v_pk_add_f32 v[90:91], v[90:91], v[94:95]
	s_waitcnt lgkmcnt(1)
	v_mov_b32_e32 v100, v97
	v_mov_b32_e32 v101, v96
	v_pk_add_f32 v[90:91], v[90:91], v[104:105]
	s_waitcnt lgkmcnt(0)
	v_mov_b32_e32 v96, v93
	v_mov_b32_e32 v97, v92
	v_pk_add_f32 v[90:91], v[90:91], v[100:101]
	v_lshl_add_u64 v[60:61], v[60:61], 0, s[48:49]
	v_pk_add_f32 v[90:91], v[90:91], v[96:97]
	v_mov_b32_e32 v109, v85
	v_pk_fma_f32 v[88:89], v[90:91], s[8:9], v[88:89] op_sel_hi:[1,0,0]
	v_lshl_add_u64 v[90:91], v[60:61], 0, v[82:83]
	v_mul_f32_e32 v73, 0x4b800000, v89
	v_cmp_gt_f32_e32 vcc, s33, v89
	v_lshlrev_b64 v[58:59], 12, v[108:109]
	v_lshl_add_u64 v[58:59], v[86:87], 0, v[58:59]
	v_cndmask_b32_e32 v73, v89, v73, vcc
	v_rsq_f32_e32 v73, v73
	v_and_b32_e32 v89, 0xffff0000, v215
	v_mul_f32_e32 v77, 0x45800000, v73
	v_cndmask_b32_e32 v82, v73, v77, vcc
	v_lshlrev_b32_e32 v73, 16, v214
	v_and_b32_e32 v77, 0xffff0000, v214
	v_pk_mul_f32 v[54:55], v[54:55], v[82:83] op_sel_hi:[1,0]
	v_pk_mul_f32 v[56:57], v[56:57], v[82:83] op_sel_hi:[1,0]
	v_lshlrev_b32_e32 v83, 16, v215
	v_mul_f32_e32 v92, 0xbfb8aa3b, v73
	v_mul_f32_e32 v93, 0xbfb8aa3b, v77
	v_mul_f32_e32 v94, 0xbfb8aa3b, v83
	v_mul_f32_e32 v95, 0xbfb8aa3b, v89
	v_exp_f32_e32 v92, v92
	v_exp_f32_e32 v93, v93
	v_exp_f32_e32 v94, v94
	v_exp_f32_e32 v95, v95
	v_add_f32_e32 v92, 1.0, v92
	v_add_f32_e32 v93, 1.0, v93
	v_add_f32_e32 v94, 1.0, v94
	v_add_f32_e32 v95, 1.0, v95
	v_rcp_f32_e32 v92, v92
	v_rcp_f32_e32 v93, v93
	v_rcp_f32_e32 v94, v94
	v_rcp_f32_e32 v95, v95
	v_pk_mul_f32 v[54:55], v[190:191], v[54:55]
	v_mul_f32_e32 v73, v92, v73
	v_mul_f32_e32 v77, v93, v77
	v_pk_mul_f32 v[56:57], v[192:193], v[56:57]
	v_mul_f32_e32 v83, v94, v83
	v_mul_f32_e32 v89, v95, v89
	v_mul_f32_e32 v54, v54, v73
	v_mul_f32_e32 v55, v55, v77
	v_mul_f32_e32 v56, v56, v83
	v_mul_f32_e32 v57, v57, v89
	v_cvt_pk_bf16_f32 v54, v54, v55
	v_cvt_pk_bf16_f32 v55, v56, v57
	global_store_dwordx2 v[58:59], v[54:55], off
	v_mul_f32_e32 v57, 0x4b800000, v88
	v_cmp_gt_f32_e32 vcc, s33, v88
	v_or_b32_e32 v56, 16, v72
	s_nop 0
	v_cndmask_b32_e32 v57, v88, v57, vcc
; __device__ __forceinline__ unsigned pk2(float lo, float hi) { return pg8::cvt_pk_bf16(lo, hi); }
; __device__ __forceinline__ float siluf(float x) { return x * __builtin_amdgcn_rcpf(1.0f + __expf(-x)); }
; template <int TY> __device__ __forceinline__ void mc_item(const Params& p, ldsp lds, int item) {
;     ...
;     for (int ei = 0; ei < ET; ++ei) { const int e0 = 16 * (wave * ET + ei) + 4 * q4; const f32x4 w4 = *(const f32x4*)(nwp + e0);
; #pragma unroll
;         for (int tk = 0; tk < 4; ++tk) { const size_t row = (size_t)row0 + 16 * tk + l15;
;             const u32x2 gw = *(const u32x2*)(Pb + row * PP + goff + e0);
;             const float g0 = bf2f(gw.x & 0xffffu), g1 = bf2f(gw.x >> 16), g2 = bf2f(gw.y & 0xffffu), g3 = bf2f(gw.y >> 16);
;             const f32x4 v = acc[ei][tk] * rstd[tk] * w4;
;             float y0 = v[0] * siluf(g0), y1 = v[1] * siluf(g1), y2 = v[2] * siluf(g2), y3 = v[3] * siluf(g3);
;     ...
;             if (!(fabsf(y0) < 1e30f)) y0 = 0.f; if (!(fabsf(y1) < 1e30f)) y1 = 0.f; if (!(fabsf(y2) < 1e30f)) y2 = 0.f; if (!(fabsf(y3) < 1e30f)) y3 = 0.f;
;     ...
;             u32x2 o; o.x = pk2(y0, y1); o.y = pk2(y2, y3);
;             *(u32x2*)(Y + row * LDY + ycol + e0) = o; } }
	v_rsq_f32_e32 v73, v57
	v_ashrrev_i32_e32 v57, 31, v56
	v_lshlrev_b64 v[88:89], 1, v[56:57]
	v_lshl_add_u64 v[90:91], v[74:75], 0, v[88:89]
	v_mul_f32_e32 v56, 0x45800000, v73
	v_cndmask_b32_e32 v56, v73, v56, vcc
	v_pk_mul_f32 v[50:51], v[50:51], v[56:57] op_sel_hi:[1,0]
	v_pk_mul_f32 v[52:53], v[52:53], v[56:57] op_sel_hi:[1,0]
	v_pk_mul_f32 v[50:51], v[190:191], v[50:51]
	v_pk_mul_f32 v[52:53], v[192:193], v[52:53]
	v_lshlrev_b32_e32 v57, 16, v222
	v_and_b32_e32 v54, 0xffff0000, v222
	v_lshlrev_b32_e32 v62, 16, v223
	v_and_b32_e32 v55, 0xffff0000, v223
	v_mul_f32_e32 v63, 0xbfb8aa3b, v57
	v_mul_f32_e32 v64, 0xbfb8aa3b, v54
	v_mul_f32_e32 v65, 0xbfb8aa3b, v62
	v_mul_f32_e32 v73, 0xbfb8aa3b, v55
	v_exp_f32_e32 v63, v63
	v_exp_f32_e32 v64, v64
	v_exp_f32_e32 v65, v65
	v_exp_f32_e32 v73, v73
	v_add_f32_e32 v63, 1.0, v63
	v_add_f32_e32 v64, 1.0, v64
	v_add_f32_e32 v65, 1.0, v65
	v_add_f32_e32 v73, 1.0, v73
	v_rcp_f32_e32 v63, v63
	v_rcp_f32_e32 v64, v64
	v_rcp_f32_e32 v65, v65
	v_rcp_f32_e32 v73, v73
	v_mul_f32_e32 v57, v63, v57
	v_mul_f32_e32 v54, v64, v54
	v_mul_f32_e32 v62, v65, v62
	v_mul_f32_e32 v55, v73, v55
	v_mul_f32_e32 v50, v50, v57
	v_mul_f32_e32 v51, v51, v54
	v_mul_f32_e32 v52, v52, v62
	v_mul_f32_e32 v53, v53, v55
	v_cvt_pk_bf16_f32 v50, v50, v51
	v_cvt_pk_bf16_f32 v51, v52, v53
	v_lshlrev_b64 v[52:53], 12, v[84:85]
	v_lshl_add_u64 v[54:55], v[86:87], 0, v[52:53]
	global_store_dwordx2 v[54:55], v[50:51], off
	v_lshl_add_u64 v[64:65], v[80:81], 0, v[88:89]
	v_lshlrev_b32_e32 v57, 16, v230
	v_and_b32_e32 v62, 0xffff0000, v230
	v_lshlrev_b32_e32 v73, 16, v231
	v_and_b32_e32 v63, 0xffff0000, v231
	v_mul_f32_e32 v77, 0xbfb8aa3b, v57
	v_mul_f32_e32 v83, 0xbfb8aa3b, v62
	v_mul_f32_e32 v84, 0xbfb8aa3b, v73
	v_mul_f32_e32 v85, 0xbfb8aa3b, v63
	v_exp_f32_e32 v77, v77
	v_exp_f32_e32 v83, v83
	v_exp_f32_e32 v84, v84
	v_exp_f32_e32 v85, v85
	v_add_f32_e32 v77, 1.0, v77
	v_add_f32_e32 v83, 1.0, v83
	v_add_f32_e32 v84, 1.0, v84
	v_add_f32_e32 v85, 1.0, v85
	v_rcp_f32_e32 v77, v77
	v_rcp_f32_e32 v83, v83
	v_rcp_f32_e32 v84, v84
	v_rcp_f32_e32 v85, v85
	v_pk_mul_f32 v[46:47], v[46:47], v[232:233]
	v_mul_f32_e32 v57, v77, v57
	v_mul_f32_e32 v62, v83, v62
	v_pk_mul_f32 v[48:49], v[48:49], v[234:235]
	v_mul_f32_e32 v73, v84, v73
	v_mul_f32_e32 v63, v85, v63
	v_mul_f32_e32 v46, v46, v57
	v_mul_f32_e32 v47, v47, v62
	v_mul_f32_e32 v48, v48, v73
	v_mul_f32_e32 v49, v49, v63
	v_cvt_pk_bf16_f32 v46, v46, v47
	v_cvt_pk_bf16_f32 v47, v48, v49
	global_store_dwordx2 v[78:79], v[46:47], off offset:32
	v_pk_mul_f32 v[42:43], v[42:43], v[76:77] op_sel_hi:[1,0]
	v_pk_mul_f32 v[44:45], v[44:45], v[76:77] op_sel_hi:[1,0]
	v_pk_mul_f32 v[42:43], v[42:43], v[232:233]
	v_pk_mul_f32 v[44:45], v[44:45], v[234:235]
	v_lshl_add_u64 v[48:49], v[68:69], 0, v[88:89]
	v_pk_mul_f32 v[38:39], v[38:39], v[82:83] op_sel_hi:[1,0]
	v_pk_mul_f32 v[40:41], v[40:41], v[82:83] op_sel_hi:[1,0]
	v_pk_mul_f32 v[38:39], v[38:39], v[232:233]
	v_pk_mul_f32 v[40:41], v[40:41], v[234:235]
	v_pk_mul_f32 v[26:27], v[26:27], v[76:77] op_sel_hi:[1,0]
	v_pk_mul_f32 v[28:29], v[28:29], v[76:77] op_sel_hi:[1,0]
	v_pk_mul_f32 v[22:23], v[22:23], v[82:83] op_sel_hi:[1,0]
	v_pk_mul_f32 v[24:25], v[24:25], v[82:83] op_sel_hi:[1,0]
	v_pk_mul_f32 v[8:9], v[8:9], v[76:77] op_sel_hi:[1,0]
	v_pk_mul_f32 v[10:11], v[10:11], v[76:77] op_sel_hi:[1,0]
	v_pk_mul_f32 v[4:5], v[4:5], v[82:83] op_sel_hi:[1,0]
	v_pk_mul_f32 v[6:7], v[6:7], v[82:83] op_sel_hi:[1,0]
	v_lshlrev_b32_e32 v57, 16, v238
	v_and_b32_e32 v46, 0xffff0000, v238
	v_lshlrev_b32_e32 v62, 16, v239
	v_and_b32_e32 v47, 0xffff0000, v239
	v_mul_f32_e32 v63, 0xbfb8aa3b, v57
	v_mul_f32_e32 v64, 0xbfb8aa3b, v46
	v_mul_f32_e32 v65, 0xbfb8aa3b, v62
	v_mul_f32_e32 v73, 0xbfb8aa3b, v47
	v_exp_f32_e32 v63, v63
	v_exp_f32_e32 v64, v64
	v_exp_f32_e32 v65, v65
	v_exp_f32_e32 v73, v73
	v_add_f32_e32 v63, 1.0, v63
	v_add_f32_e32 v64, 1.0, v64
	v_add_f32_e32 v65, 1.0, v65
	v_add_f32_e32 v73, 1.0, v73
	v_rcp_f32_e32 v63, v63
	v_rcp_f32_e32 v64, v64
	v_rcp_f32_e32 v65, v65
	v_rcp_f32_e32 v73, v73
	v_mul_f32_e32 v57, v63, v57
	v_mul_f32_e32 v46, v64, v46
	v_mul_f32_e32 v62, v65, v62
	v_mul_f32_e32 v47, v73, v47
	v_mul_f32_e32 v42, v42, v57
	v_mul_f32_e32 v43, v43, v46
	v_mul_f32_e32 v44, v44, v62
	v_mul_f32_e32 v45, v45, v47
	v_cvt_pk_bf16_f32 v42, v42, v43
	v_cvt_pk_bf16_f32 v43, v44, v45
	global_store_dwordx2 v[66:67], v[42:43], off offset:32
	v_lshl_add_u64 v[44:45], v[60:61], 0, v[88:89]
	v_lshlrev_b32_e32 v46, 16, v242
	v_and_b32_e32 v42, 0xffff0000, v242
	v_lshlrev_b32_e32 v47, 16, v243
	v_and_b32_e32 v43, 0xffff0000, v243
	v_mul_f32_e32 v48, 0xbfb8aa3b, v46
	v_mul_f32_e32 v49, 0xbfb8aa3b, v42
	v_mul_f32_e32 v57, 0xbfb8aa3b, v47
	v_mul_f32_e32 v62, 0xbfb8aa3b, v43
	v_exp_f32_e32 v48, v48
	v_exp_f32_e32 v49, v49
	v_exp_f32_e32 v57, v57
	v_exp_f32_e32 v62, v62
	v_add_f32_e32 v48, 1.0, v48
	v_add_f32_e32 v49, 1.0, v49
	v_add_f32_e32 v57, 1.0, v57
	v_add_f32_e32 v62, 1.0, v62
	v_rcp_f32_e32 v48, v48
	v_rcp_f32_e32 v49, v49
	v_rcp_f32_e32 v57, v57
	v_rcp_f32_e32 v62, v62
	v_mul_f32_e32 v46, v48, v46
	v_mul_f32_e32 v42, v49, v42
	v_mul_f32_e32 v47, v57, v47
	v_mul_f32_e32 v43, v62, v43
	v_mul_f32_e32 v38, v38, v46
	v_mul_f32_e32 v39, v39, v42
	v_mul_f32_e32 v40, v40, v47
	v_mul_f32_e32 v41, v41, v43
	v_cvt_pk_bf16_f32 v38, v38, v39
	v_cvt_pk_bf16_f32 v39, v40, v41
	global_store_dwordx2 v[58:59], v[38:39], off offset:32
	v_or_b32_e32 v38, 32, v72
	v_ashrrev_i32_e32 v39, 31, v38
	v_pk_mul_f32 v[34:35], v[34:35], v[56:57] op_sel_hi:[1,0]
	v_lshlrev_b64 v[38:39], 1, v[38:39]
	v_pk_mul_f32 v[36:37], v[36:37], v[56:57] op_sel_hi:[1,0]
	v_pk_mul_f32 v[34:35], v[34:35], v[232:233]
; __device__ __forceinline__ unsigned pk2(float lo, float hi) { return pg8::cvt_pk_bf16(lo, hi); }
; __device__ __forceinline__ float siluf(float x) { return x * __builtin_amdgcn_rcpf(1.0f + __expf(-x)); }
; template <int TY> __device__ __forceinline__ void mc_item(const Params& p, ldsp lds, int item) {
;     ...
;     for (int ei = 0; ei < ET; ++ei) { const int e0 = 16 * (wave * ET + ei) + 4 * q4; const f32x4 w4 = *(const f32x4*)(nwp + e0);
; #pragma unroll
;         for (int tk = 0; tk < 4; ++tk) { const size_t row = (size_t)row0 + 16 * tk + l15;
;             const u32x2 gw = *(const u32x2*)(Pb + row * PP + goff + e0);
;             const float g0 = bf2f(gw.x & 0xffffu), g1 = bf2f(gw.x >> 16), g2 = bf2f(gw.y & 0xffffu), g3 = bf2f(gw.y >> 16);
;             const f32x4 v = acc[ei][tk] * rstd[tk] * w4;
;             float y0 = v[0] * siluf(g0), y1 = v[1] * siluf(g1), y2 = v[2] * siluf(g2), y3 = v[3] * siluf(g3);
;     ...
;             if (!(fabsf(y0) < 1e30f)) y0 = 0.f; if (!(fabsf(y1) < 1e30f)) y1 = 0.f; if (!(fabsf(y2) < 1e30f)) y2 = 0.f; if (!(fabsf(y3) < 1e30f)) y3 = 0.f;
;     ...
;             u32x2 o; o.x = pk2(y0, y1); o.y = pk2(y2, y3);
;             *(u32x2*)(Y + row * LDY + ycol + e0) = o; } }
	v_lshl_add_u64 v[42:43], v[74:75], 0, v[38:39]
	v_pk_mul_f32 v[36:37], v[36:37], v[234:235]
	v_pk_mul_f32 v[18:19], v[18:19], v[56:57] op_sel_hi:[1,0]
	v_pk_mul_f32 v[20:21], v[20:21], v[56:57] op_sel_hi:[1,0]
	v_pk_mul_f32 v[0:1], v[0:1], v[56:57] op_sel_hi:[1,0]
	v_pk_mul_f32 v[2:3], v[2:3], v[56:57] op_sel_hi:[1,0]
	v_lshlrev_b32_e32 v44, 16, v246
	v_and_b32_e32 v40, 0xffff0000, v246
	v_lshlrev_b32_e32 v45, 16, v247
	v_and_b32_e32 v41, 0xffff0000, v247
	v_mul_f32_e32 v46, 0xbfb8aa3b, v44
	v_mul_f32_e32 v47, 0xbfb8aa3b, v40
	v_mul_f32_e32 v48, 0xbfb8aa3b, v45
	v_mul_f32_e32 v49, 0xbfb8aa3b, v41
	v_exp_f32_e32 v46, v46
	v_exp_f32_e32 v47, v47
	v_exp_f32_e32 v48, v48
	v_exp_f32_e32 v49, v49
	v_add_f32_e32 v46, 1.0, v46
	v_add_f32_e32 v47, 1.0, v47
	v_add_f32_e32 v48, 1.0, v48
	v_add_f32_e32 v49, 1.0, v49
	v_rcp_f32_e32 v46, v46
	v_rcp_f32_e32 v47, v47
	v_rcp_f32_e32 v48, v48
	v_rcp_f32_e32 v49, v49
	v_mul_f32_e32 v44, v46, v44
	v_mul_f32_e32 v40, v47, v40
	v_mul_f32_e32 v45, v48, v45
	v_mul_f32_e32 v41, v49, v41
	v_mul_f32_e32 v34, v34, v44
	v_mul_f32_e32 v35, v35, v40
	v_mul_f32_e32 v36, v36, v45
	v_mul_f32_e32 v37, v37, v41
	v_cvt_pk_bf16_f32 v34, v34, v35
	v_cvt_pk_bf16_f32 v35, v36, v37
	v_lshl_add_u64 v[42:43], v[80:81], 0, v[38:39]
	global_store_dwordx2 v[54:55], v[34:35], off offset:32
	v_lshlrev_b32_e32 v44, 16, v124
	v_and_b32_e32 v40, 0xffff0000, v124
	v_lshlrev_b32_e32 v45, 16, v125
	v_and_b32_e32 v41, 0xffff0000, v125
	v_mul_f32_e32 v46, 0xbfb8aa3b, v44
	v_mul_f32_e32 v47, 0xbfb8aa3b, v40
	v_mul_f32_e32 v48, 0xbfb8aa3b, v45
	v_mul_f32_e32 v49, 0xbfb8aa3b, v41
	v_exp_f32_e32 v46, v46
	v_exp_f32_e32 v47, v47
	v_exp_f32_e32 v48, v48
	v_exp_f32_e32 v49, v49
	v_add_f32_e32 v46, 1.0, v46
	v_add_f32_e32 v47, 1.0, v47
	v_add_f32_e32 v48, 1.0, v48
	v_add_f32_e32 v49, 1.0, v49
	v_rcp_f32_e32 v46, v46
	v_rcp_f32_e32 v47, v47
	v_rcp_f32_e32 v48, v48
	v_rcp_f32_e32 v49, v49
	v_pk_mul_f32 v[30:31], v[30:31], v[128:129]
	v_mul_f32_e32 v44, v46, v44
	v_mul_f32_e32 v40, v47, v40
	v_pk_mul_f32 v[32:33], v[32:33], v[130:131]
	v_mul_f32_e32 v45, v48, v45
	v_mul_f32_e32 v41, v49, v41
	v_mul_f32_e32 v30, v30, v44
	v_mul_f32_e32 v31, v31, v40
	v_mul_f32_e32 v32, v32, v45
	v_mul_f32_e32 v33, v33, v41
	v_cvt_pk_bf16_f32 v30, v30, v31
	v_cvt_pk_bf16_f32 v31, v32, v33
	global_store_dwordx2 v[78:79], v[30:31], off offset:64
	v_pk_mul_f32 v[26:27], v[26:27], v[128:129]
	v_pk_mul_f32 v[28:29], v[28:29], v[130:131]
	v_lshl_add_u64 v[32:33], v[68:69], 0, v[38:39]
	v_pk_mul_f32 v[22:23], v[22:23], v[128:129]
	v_pk_mul_f32 v[24:25], v[24:25], v[130:131]
	v_pk_mul_f32 v[18:19], v[18:19], v[128:129]
	v_pk_mul_f32 v[20:21], v[20:21], v[130:131]
	v_lshlrev_b32_e32 v40, 16, v132
	v_and_b32_e32 v30, 0xffff0000, v132
	v_lshlrev_b32_e32 v41, 16, v133
	v_and_b32_e32 v31, 0xffff0000, v133
	v_mul_f32_e32 v42, 0xbfb8aa3b, v40
	v_mul_f32_e32 v43, 0xbfb8aa3b, v30
	v_mul_f32_e32 v44, 0xbfb8aa3b, v41
	v_mul_f32_e32 v45, 0xbfb8aa3b, v31
	v_exp_f32_e32 v42, v42
	v_exp_f32_e32 v43, v43
	v_exp_f32_e32 v44, v44
	v_exp_f32_e32 v45, v45
	v_add_f32_e32 v42, 1.0, v42
	v_add_f32_e32 v43, 1.0, v43
	v_add_f32_e32 v44, 1.0, v44
	v_add_f32_e32 v45, 1.0, v45
	v_rcp_f32_e32 v42, v42
	v_rcp_f32_e32 v43, v43
	v_rcp_f32_e32 v44, v44
	v_rcp_f32_e32 v45, v45
	v_mul_f32_e32 v40, v42, v40
	v_mul_f32_e32 v30, v43, v30
	v_mul_f32_e32 v41, v44, v41
	v_mul_f32_e32 v31, v45, v31
	v_mul_f32_e32 v26, v26, v40
	v_mul_f32_e32 v27, v27, v30
	v_mul_f32_e32 v28, v28, v41
	v_mul_f32_e32 v29, v29, v31
	v_cvt_pk_bf16_f32 v26, v26, v27
	v_cvt_pk_bf16_f32 v27, v28, v29
	global_store_dwordx2 v[66:67], v[26:27], off offset:64
	v_lshl_add_u64 v[28:29], v[60:61], 0, v[38:39]
	v_lshlrev_b32_e32 v30, 16, v136
	v_and_b32_e32 v26, 0xffff0000, v136
	v_lshlrev_b32_e32 v31, 16, v137
	v_and_b32_e32 v27, 0xffff0000, v137
	v_mul_f32_e32 v32, 0xbfb8aa3b, v30
	v_mul_f32_e32 v33, 0xbfb8aa3b, v26
	v_mul_f32_e32 v38, 0xbfb8aa3b, v31
	v_mul_f32_e32 v39, 0xbfb8aa3b, v27
	v_exp_f32_e32 v32, v32
	v_exp_f32_e32 v33, v33
	v_exp_f32_e32 v38, v38
	v_exp_f32_e32 v39, v39
	v_add_f32_e32 v32, 1.0, v32
	v_add_f32_e32 v33, 1.0, v33
	v_add_f32_e32 v38, 1.0, v38
	v_add_f32_e32 v39, 1.0, v39
	v_rcp_f32_e32 v32, v32
	v_rcp_f32_e32 v33, v33
	v_rcp_f32_e32 v38, v38
	v_rcp_f32_e32 v39, v39
	v_mul_f32_e32 v30, v32, v30
	v_mul_f32_e32 v26, v33, v26
	v_mul_f32_e32 v31, v38, v31
	v_mul_f32_e32 v27, v39, v27
	v_mul_f32_e32 v22, v22, v30
	v_mul_f32_e32 v23, v23, v26
	v_mul_f32_e32 v24, v24, v31
	v_mul_f32_e32 v25, v25, v27
	v_cvt_pk_bf16_f32 v22, v22, v23
	v_cvt_pk_bf16_f32 v23, v24, v25
	global_store_dwordx2 v[58:59], v[22:23], off offset:64
	v_or_b32_e32 v22, 48, v72
	v_ashrrev_i32_e32 v23, 31, v22
	v_lshlrev_b64 v[22:23], 1, v[22:23]
	v_lshl_add_u64 v[26:27], v[74:75], 0, v[22:23]
	v_lshlrev_b32_e32 v28, 16, v142
	v_and_b32_e32 v24, 0xffff0000, v142
	v_lshlrev_b32_e32 v29, 16, v143
	v_and_b32_e32 v25, 0xffff0000, v143
	v_mul_f32_e32 v30, 0xbfb8aa3b, v28
	v_mul_f32_e32 v31, 0xbfb8aa3b, v24
	v_mul_f32_e32 v32, 0xbfb8aa3b, v29
	v_mul_f32_e32 v33, 0xbfb8aa3b, v25
	v_exp_f32_e32 v30, v30
	v_exp_f32_e32 v31, v31
	v_exp_f32_e32 v32, v32
	v_exp_f32_e32 v33, v33
	v_add_f32_e32 v30, 1.0, v30
; __device__ __forceinline__ unsigned pk2(float lo, float hi) { return pg8::cvt_pk_bf16(lo, hi); }
; __device__ __forceinline__ float siluf(float x) { return x * __builtin_amdgcn_rcpf(1.0f + __expf(-x)); }
; template <int TY> __device__ __forceinline__ void mc_item(const Params& p, ldsp lds, int item) {
;     ...
;     for (int ei = 0; ei < ET; ++ei) { const int e0 = 16 * (wave * ET + ei) + 4 * q4; const f32x4 w4 = *(const f32x4*)(nwp + e0);
; #pragma unroll
;         for (int tk = 0; tk < 4; ++tk) { const size_t row = (size_t)row0 + 16 * tk + l15;
;             const u32x2 gw = *(const u32x2*)(Pb + row * PP + goff + e0);
;             const float g0 = bf2f(gw.x & 0xffffu), g1 = bf2f(gw.x >> 16), g2 = bf2f(gw.y & 0xffffu), g3 = bf2f(gw.y >> 16);
;             const f32x4 v = acc[ei][tk] * rstd[tk] * w4;
;             float y0 = v[0] * siluf(g0), y1 = v[1] * siluf(g1), y2 = v[2] * siluf(g2), y3 = v[3] * siluf(g3);
;     ...
;             if (!(fabsf(y0) < 1e30f)) y0 = 0.f; if (!(fabsf(y1) < 1e30f)) y1 = 0.f; if (!(fabsf(y2) < 1e30f)) y2 = 0.f; if (!(fabsf(y3) < 1e30f)) y3 = 0.f;
;     ...
;             u32x2 o; o.x = pk2(y0, y1); o.y = pk2(y2, y3);
;             *(u32x2*)(Y + row * LDY + ycol + e0) = o; } }
	v_add_f32_e32 v31, 1.0, v31
	v_add_f32_e32 v32, 1.0, v32
	v_add_f32_e32 v33, 1.0, v33
	v_rcp_f32_e32 v30, v30
	v_rcp_f32_e32 v31, v31
	v_rcp_f32_e32 v32, v32
	v_rcp_f32_e32 v33, v33
	v_mul_f32_e32 v28, v30, v28
	v_mul_f32_e32 v24, v31, v24
	v_mul_f32_e32 v29, v32, v29
	v_mul_f32_e32 v25, v33, v25
	v_mul_f32_e32 v18, v18, v28
	v_mul_f32_e32 v19, v19, v24
	v_mul_f32_e32 v20, v20, v29
	v_mul_f32_e32 v21, v21, v25
	v_cvt_pk_bf16_f32 v18, v18, v19
	v_cvt_pk_bf16_f32 v19, v20, v21
	v_lshl_add_u64 v[26:27], v[80:81], 0, v[22:23]
	global_store_dwordx2 v[54:55], v[18:19], off offset:64
	v_lshlrev_b32_e32 v16, 16, v154
	v_and_b32_e32 v24, 0xffff0000, v154
	v_lshlrev_b32_e32 v28, 16, v155
	v_and_b32_e32 v25, 0xffff0000, v155
	v_mul_f32_e32 v29, 0xbfb8aa3b, v16
	v_mul_f32_e32 v30, 0xbfb8aa3b, v24
	v_mul_f32_e32 v31, 0xbfb8aa3b, v28
	v_mul_f32_e32 v32, 0xbfb8aa3b, v25
	v_exp_f32_e32 v29, v29
	v_exp_f32_e32 v30, v30
	v_exp_f32_e32 v31, v31
	v_exp_f32_e32 v32, v32
	v_add_f32_e32 v29, 1.0, v29
	v_add_f32_e32 v30, 1.0, v30
	v_add_f32_e32 v31, 1.0, v31
	v_add_f32_e32 v32, 1.0, v32
	v_rcp_f32_e32 v29, v29
	v_rcp_f32_e32 v30, v30
	v_rcp_f32_e32 v31, v31
	v_rcp_f32_e32 v32, v32
	v_pk_mul_f32 v[12:13], v[12:13], v[172:173]
	v_mul_f32_e32 v16, v29, v16
	v_mul_f32_e32 v24, v30, v24
	v_pk_mul_f32 v[14:15], v[14:15], v[174:175]
	v_mul_f32_e32 v28, v31, v28
	v_mul_f32_e32 v25, v32, v25
	v_mul_f32_e32 v12, v12, v16
	v_mul_f32_e32 v13, v13, v24
	v_mul_f32_e32 v14, v14, v28
	v_mul_f32_e32 v15, v15, v25
	v_cvt_pk_bf16_f32 v12, v12, v13
	v_cvt_pk_bf16_f32 v13, v14, v15
	global_store_dwordx2 v[78:79], v[12:13], off offset:96
	v_pk_mul_f32 v[8:9], v[8:9], v[172:173]
	v_pk_mul_f32 v[10:11], v[10:11], v[174:175]
	v_lshl_add_u64 v[14:15], v[68:69], 0, v[22:23]
	v_pk_mul_f32 v[4:5], v[4:5], v[172:173]
	v_pk_mul_f32 v[6:7], v[6:7], v[174:175]
	v_pk_mul_f32 v[0:1], v[0:1], v[172:173]
	v_pk_mul_f32 v[2:3], v[2:3], v[174:175]
	v_lshlrev_b32_e32 v16, 16, v158
	v_and_b32_e32 v12, 0xffff0000, v158
	v_lshlrev_b32_e32 v24, 16, v159
	v_and_b32_e32 v13, 0xffff0000, v159
	v_mul_f32_e32 v25, 0xbfb8aa3b, v16
	v_mul_f32_e32 v26, 0xbfb8aa3b, v12
	v_mul_f32_e32 v27, 0xbfb8aa3b, v24
	v_mul_f32_e32 v28, 0xbfb8aa3b, v13
	v_exp_f32_e32 v25, v25
	v_exp_f32_e32 v26, v26
	v_exp_f32_e32 v27, v27
	v_exp_f32_e32 v28, v28
	v_add_f32_e32 v25, 1.0, v25
	v_add_f32_e32 v26, 1.0, v26
	v_add_f32_e32 v27, 1.0, v27
	v_add_f32_e32 v28, 1.0, v28
	v_rcp_f32_e32 v25, v25
	v_rcp_f32_e32 v26, v26
	v_rcp_f32_e32 v27, v27
	v_rcp_f32_e32 v28, v28
	v_mul_f32_e32 v16, v25, v16
	v_mul_f32_e32 v12, v26, v12
	v_mul_f32_e32 v24, v27, v24
	v_mul_f32_e32 v13, v28, v13
	v_mul_f32_e32 v8, v8, v16
	v_mul_f32_e32 v9, v9, v12
	v_mul_f32_e32 v10, v10, v24
	v_mul_f32_e32 v11, v11, v13
	v_cvt_pk_bf16_f32 v8, v8, v9
	v_cvt_pk_bf16_f32 v9, v10, v11
	global_store_dwordx2 v[66:67], v[8:9], off offset:96
	v_lshl_add_u64 v[10:11], v[60:61], 0, v[22:23]
	v_lshlrev_b32_e32 v12, 16, v166
	v_and_b32_e32 v8, 0xffff0000, v166
	v_lshlrev_b32_e32 v13, 16, v167
	v_and_b32_e32 v9, 0xffff0000, v167
	v_mul_f32_e32 v14, 0xbfb8aa3b, v12
	v_mul_f32_e32 v15, 0xbfb8aa3b, v8
	v_mul_f32_e32 v16, 0xbfb8aa3b, v13
	v_mul_f32_e32 v22, 0xbfb8aa3b, v9
	v_exp_f32_e32 v14, v14
	v_exp_f32_e32 v15, v15
	v_exp_f32_e32 v16, v16
	v_exp_f32_e32 v22, v22
	v_add_f32_e32 v14, 1.0, v14
	v_add_f32_e32 v15, 1.0, v15
	v_add_f32_e32 v16, 1.0, v16
	v_add_f32_e32 v22, 1.0, v22
	v_rcp_f32_e32 v14, v14
	v_rcp_f32_e32 v15, v15
	v_rcp_f32_e32 v16, v16
	v_rcp_f32_e32 v22, v22
	v_mul_f32_e32 v12, v14, v12
	v_mul_f32_e32 v8, v15, v8
	v_mul_f32_e32 v13, v16, v13
	v_mul_f32_e32 v9, v22, v9
	v_mul_f32_e32 v4, v4, v12
	v_mul_f32_e32 v5, v5, v8
	v_mul_f32_e32 v6, v6, v13
	v_mul_f32_e32 v7, v7, v9
	v_cvt_pk_bf16_f32 v4, v4, v5
	v_cvt_pk_bf16_f32 v5, v6, v7
	global_store_dwordx2 v[58:59], v[4:5], off offset:96
	v_lshlrev_b32_e32 v6, 16, v178
	v_and_b32_e32 v4, 0xffff0000, v178
	v_lshlrev_b32_e32 v7, 16, v179
	v_and_b32_e32 v5, 0xffff0000, v179
	v_mul_f32_e32 v8, 0xbfb8aa3b, v6
	v_mul_f32_e32 v9, 0xbfb8aa3b, v4
	v_mul_f32_e32 v10, 0xbfb8aa3b, v7
	v_mul_f32_e32 v11, 0xbfb8aa3b, v5
	v_exp_f32_e32 v8, v8
	v_exp_f32_e32 v9, v9
	v_exp_f32_e32 v10, v10
	v_exp_f32_e32 v11, v11
	v_add_f32_e32 v8, 1.0, v8
	v_add_f32_e32 v9, 1.0, v9
	v_add_f32_e32 v10, 1.0, v10
	v_add_f32_e32 v11, 1.0, v11
	v_rcp_f32_e32 v8, v8
	v_rcp_f32_e32 v9, v9
	v_rcp_f32_e32 v10, v10
	v_rcp_f32_e32 v11, v11
	v_mul_f32_e32 v6, v8, v6
	v_mul_f32_e32 v4, v9, v4
	v_mul_f32_e32 v7, v10, v7
	v_mul_f32_e32 v5, v11, v5
	v_mul_f32_e32 v0, v0, v6
	v_mul_f32_e32 v1, v1, v4
	v_mul_f32_e32 v2, v2, v7
	v_mul_f32_e32 v3, v3, v5
	v_cvt_pk_bf16_f32 v0, v0, v1
	v_cvt_pk_bf16_f32 v1, v2, v3
	global_store_dwordx2 v[54:55], v[0:1], off offset:96
	v_mov_b32_e32 v18, v172
	v_mov_b32_e32 v19, v173
	v_mov_b32_e32 v20, v174
	v_mov_b32_e32 v21, v175
	v_mov_b32_e32 v34, v128
	v_mov_b32_e32 v35, v129
	v_mov_b32_e32 v36, v130
	v_mov_b32_e32 v37, v131
	v_mov_b32_e32 v50, v232
	v_mov_b32_e32 v51, v233
	v_mov_b32_e32 v52, v234
	v_mov_b32_e32 v53, v235
	v_mov_b32_e32 v110, v214
	v_mov_b32_e32 v111, v215
	s_waitcnt vmcnt(0) lgkmcnt(0)
	s_barrier
	s_cbranch_scc0 .LBB0_853
